# v26 + attention loops: row-max via permlane16/32 swaps, QK first-MFMA accumulates in place (no SrcC overlap nops); stagger dropped
# speedup vs baseline: 1.0749x; 1.0036x over previous
.LBB0_698:
	s_mul_i32 s23, s23, 0x8c00
	v_add_u32_e32 v220, s23, v218
	v_add_u32_e32 v113, s23, v219
	ds_read_b128 v[114:117], v113
	ds_read_b128 v[118:121], v113 offset:64
	s_waitcnt lgkmcnt(1)
	v_mfma_f32_16x16x32_bf16 v[144:147], v[114:117], v[16:19], 0
	s_waitcnt lgkmcnt(0)
	v_mfma_f32_16x16x32_bf16 v[144:147], v[118:121], v[24:27], v[144:147]
	ds_read_b128 v[118:121], v113 offset:4416
	s_nop 4
	ds_read_b128 v[114:117], v113 offset:4352
	s_waitcnt lgkmcnt(0)
	v_mfma_f32_16x16x32_bf16 v[154:157], v[114:117], v[16:19], 0
	v_mfma_f32_16x16x32_bf16 v[154:157], v[118:121], v[24:27], v[154:157]
	s_nop 6
	ds_read_b128 v[114:117], v113 offset:8704
	ds_read_b128 v[118:121], v113 offset:8768
	s_waitcnt lgkmcnt(1)
	v_mfma_f32_16x16x32_bf16 v[222:225], v[114:117], v[16:19], 0
	s_waitcnt lgkmcnt(0)
	v_mfma_f32_16x16x32_bf16 v[222:225], v[118:121], v[24:27], v[222:225]
	ds_read_b128 v[118:121], v113 offset:13120
	s_nop 4
	ds_read_b128 v[114:117], v113 offset:13056
	s_waitcnt lgkmcnt(0)
	v_mfma_f32_16x16x32_bf16 v[226:229], v[114:117], v[16:19], 0
	v_mfma_f32_16x16x32_bf16 v[226:229], v[118:121], v[24:27], v[226:229]
	s_nop 6
	ds_read_b128 v[114:117], v113 offset:128
	ds_read_b128 v[118:121], v113 offset:192
	ds_read_b128 v[122:125], v113 offset:4480
	s_waitcnt lgkmcnt(2)
	v_mfma_f32_16x16x32_bf16 v[128:131], v[114:117], v[32:35], 0
	s_waitcnt lgkmcnt(1)
	v_mfma_f32_16x16x32_bf16 v[128:131], v[118:121], v[36:39], v[128:131]
	s_nop 5
	ds_read_b128 v[114:117], v113 offset:4544
	s_waitcnt lgkmcnt(1)
	v_mfma_f32_16x16x32_bf16 v[122:125], v[122:125], v[32:35], 0
	s_waitcnt lgkmcnt(0)
	v_mfma_f32_16x16x32_bf16 v[120:123], v[114:117], v[36:39], v[122:125]
	ds_read_b128 v[114:117], v113 offset:8832
	s_nop 4
	ds_read_b128 v[124:127], v113 offset:8896
	s_waitcnt lgkmcnt(1)
	v_mfma_f32_16x16x32_bf16 v[114:117], v[114:117], v[32:35], 0
	s_waitcnt lgkmcnt(0)
	v_mfma_f32_16x16x32_bf16 v[116:119], v[124:127], v[36:39], v[114:117]
	ds_read_b128 v[124:127], v113 offset:13248
	ds_read_b128 v[172:175], v113 offset:13184
	s_waitcnt lgkmcnt(0)
	v_mfma_f32_16x16x32_bf16 v[172:175], v[172:175], v[32:35], 0
	v_mfma_f32_16x16x32_bf16 v[124:127], v[124:127], v[36:39], v[172:175]
	v_max3_f32 v113, v144, s8, v145
	v_max3_f32 v113, v113, v146, v147
	v_max3_f32 v113, v113, v154, v155
	v_max3_f32 v113, v113, v156, v157
	v_max3_f32 v113, v113, v222, v223
	v_max3_f32 v113, v113, v224, v225
	v_max3_f32 v113, v113, v226, v227
	v_max3_f32 v113, v113, v228, v229
	v_mov_b32_e32 v114, v113
	s_nop 1
	v_permlane32_swap_b32_e32 v114, v113
	s_waitcnt lgkmcnt(0)
	v_max_f32_e32 v114, v114, v114
	v_max_f32_e32 v113, v113, v114
	v_mov_b32_e32 v114, v113
	s_nop 1
	v_permlane16_swap_b32_e32 v114, v113
	s_waitcnt lgkmcnt(0)
	v_max3_f32 v221, v112, v113, v114
	v_sub_f32_e32 v114, v145, v221
	v_mul_f32_e32 v114, 0x3fb8aa3b, v114
	v_exp_f32_e32 v148, v114
	v_sub_f32_e32 v114, v146, v221
	v_sub_f32_e32 v113, v144, v221
	v_mul_f32_e32 v114, 0x3fb8aa3b, v114
	v_mul_f32_e32 v113, 0x3fb8aa3b, v113
	v_exp_f32_e32 v146, v114
	v_sub_f32_e32 v114, v147, v221
	v_exp_f32_e32 v144, v113
	v_mul_f32_e32 v114, 0x3fb8aa3b, v114
	v_exp_f32_e32 v152, v114
	v_sub_f32_e32 v114, v154, v221
	v_mul_f32_e32 v114, 0x3fb8aa3b, v114
	v_exp_f32_e32 v154, v114
	v_sub_f32_e32 v114, v155, v221
	v_add_f32_e32 v113, 0, v144
	v_mul_f32_e32 v114, 0x3fb8aa3b, v114
	v_add_f32_e32 v113, v148, v113
	v_exp_f32_e32 v158, v114
	v_add_f32_e32 v113, v146, v113
	v_add_f32_e32 v113, v152, v113
	v_add_f32_e32 v113, v154, v113
	v_add_f32_e32 v177, v158, v113
	v_sub_f32_e32 v113, v156, v221
	v_mul_f32_e32 v113, 0x3fb8aa3b, v113
	v_exp_f32_e32 v155, v113
	v_sub_f32_e32 v113, v157, v221
	v_mul_f32_e32 v113, 0x3fb8aa3b, v113
	v_exp_f32_e32 v173, v113
	v_sub_f32_e32 v113, v222, v221
	v_mul_f32_e32 v113, 0x3fb8aa3b, v113
	v_exp_f32_e32 v143, v113
	v_sub_f32_e32 v113, v223, v221
	v_mul_f32_e32 v113, 0x3fb8aa3b, v113
	v_exp_f32_e32 v147, v113
	v_sub_f32_e32 v113, v224, v221
	v_mul_f32_e32 v113, 0x3fb8aa3b, v113
	v_exp_f32_e32 v145, v113
	v_sub_f32_e32 v113, v225, v221
	v_mul_f32_e32 v113, 0x3fb8aa3b, v113
	v_exp_f32_e32 v153, v113
	v_sub_f32_e32 v113, v226, v221
	v_mul_f32_e32 v113, 0x3fb8aa3b, v113
	v_exp_f32_e32 v149, v113
	v_sub_f32_e32 v113, v227, v221
	v_mul_f32_e32 v113, 0x3fb8aa3b, v113
	v_exp_f32_e32 v159, v113
	v_sub_f32_e32 v113, v228, v221
	v_sub_f32_e32 v112, v112, v221
	v_mul_f32_e32 v113, 0x3fb8aa3b, v113
	v_mul_f32_e32 v112, 0x3fb8aa3b, v112
	v_exp_f32_e32 v157, v113
	v_sub_f32_e32 v113, v229, v221
	v_mul_f32_e32 v113, 0x3fb8aa3b, v113
	v_exp_f32_e32 v160, v112
	v_exp_f32_e32 v175, v113
	v_bfe_u32 v176, v144, 16, 1
	v_add3_u32 v231, v144, v176, s94
	v_pk_mul_f32 v[112:113], v[108:109], v[160:161] op_sel_hi:[1,0]
	v_pk_mul_f32 v[108:109], v[104:105], v[160:161] op_sel_hi:[1,0]
	v_pk_mul_f32 v[104:105], v[100:101], v[160:161] op_sel_hi:[1,0]
	v_pk_mul_f32 v[100:101], v[92:93], v[160:161] op_sel_hi:[1,0]
	v_pk_mul_f32 v[92:93], v[96:97], v[160:161] op_sel_hi:[1,0]
	v_max3_f32 v96, v128, s8, v129
	v_max3_f32 v96, v96, v130, v131
	v_max3_f32 v96, v96, v120, v121
	v_max3_f32 v96, v96, v122, v123
	v_max3_f32 v96, v96, v116, v117
	v_max3_f32 v96, v96, v118, v119
	v_max3_f32 v96, v96, v124, v125
	v_cvt_pk_bf16_f32 v237, v155, v173
	v_max3_f32 v96, v96, v126, v127
	v_cvt_pk_bf16_f32 v229, v157, v175
	v_mov_b32_e32 v97, v96
	s_nop 1
	v_permlane32_swap_b32_e32 v97, v96
	v_pk_mul_f32 v[114:115], v[110:111], v[160:161] op_sel_hi:[1,0]
	v_pk_mul_f32 v[110:111], v[106:107], v[160:161] op_sel_hi:[1,0]
	v_pk_mul_f32 v[106:107], v[102:103], v[160:161] op_sel_hi:[1,0]
	v_pk_mul_f32 v[102:103], v[94:95], v[160:161] op_sel_hi:[1,0]
	s_waitcnt lgkmcnt(0)
	v_max_f32_e32 v97, v97, v97
	v_max_f32_e32 v96, v96, v97
	v_mov_b32_e32 v97, v96
	s_nop 1
	v_permlane16_swap_b32_e32 v97, v96
	v_pk_mul_f32 v[94:95], v[98:99], v[160:161] op_sel_hi:[1,0]
	s_waitcnt lgkmcnt(0)
	v_max3_f32 v222, v142, v96, v97
	v_sub_f32_e32 v98, v129, v222
	v_mul_f32_e32 v98, 0x3fb8aa3b, v98
	v_exp_f32_e32 v129, v98
	v_sub_f32_e32 v98, v130, v222
	v_sub_f32_e32 v97, v128, v222
	v_mul_f32_e32 v98, 0x3fb8aa3b, v98
	v_mul_f32_e32 v97, 0x3fb8aa3b, v97
	v_exp_f32_e32 v130, v98
	v_sub_f32_e32 v98, v131, v222
	v_exp_f32_e32 v128, v97
	v_mul_f32_e32 v98, 0x3fb8aa3b, v98
	v_exp_f32_e32 v131, v98
	v_sub_f32_e32 v98, v120, v222
	v_mul_f32_e32 v98, 0x3fb8aa3b, v98
	v_exp_f32_e32 v239, v98
	v_sub_f32_e32 v98, v121, v222
	v_add_f32_e32 v97, 0, v128
	v_mul_f32_e32 v98, 0x3fb8aa3b, v98
	v_add_f32_e32 v97, v129, v97
	v_exp_f32_e32 v240, v98
	v_add_f32_e32 v97, v130, v97
	v_add_f32_e32 v97, v131, v97
	v_add_f32_e32 v97, v239, v97
	v_add_f32_e32 v176, v240, v97
	v_sub_f32_e32 v97, v122, v222
	v_mul_f32_e32 v97, 0x3fb8aa3b, v97
	v_cvt_pk_bf16_f32 v235, v154, v158
	v_exp_f32_e32 v154, v97
	v_sub_f32_e32 v97, v123, v222
	v_bfe_u32 v172, v146, 16, 1
	v_mul_f32_e32 v97, 0x3fb8aa3b, v97
	v_add3_u32 v233, v146, v172, s94
	v_exp_f32_e32 v172, v97
	v_sub_f32_e32 v97, v116, v222
	v_mul_f32_e32 v97, 0x3fb8aa3b, v97
	v_sub_f32_e32 v96, v142, v222
	v_exp_f32_e32 v142, v97
	v_sub_f32_e32 v97, v117, v222
	v_mul_f32_e32 v97, 0x3fb8aa3b, v97
	v_exp_f32_e32 v146, v97
	v_sub_f32_e32 v97, v118, v222
	v_mul_f32_e32 v97, 0x3fb8aa3b, v97
	v_bfe_u32 v156, v152, 16, 1
	v_cvt_pk_bf16_f32 v226, v145, v153
	v_exp_f32_e32 v144, v97
	v_sub_f32_e32 v97, v119, v222
	v_add3_u32 v234, v152, v156, s94
	v_mul_f32_e32 v97, 0x3fb8aa3b, v97
	v_bfe_u32 v174, v148, 16, 1
	v_exp_f32_e32 v152, v97
	v_sub_f32_e32 v97, v124, v222
	v_add3_u32 v232, v148, v174, s94
	v_mul_f32_e32 v97, 0x3fb8aa3b, v97
	v_cvt_pk_bf16_f32 v224, v143, v147
	v_exp_f32_e32 v148, v97
	v_sub_f32_e32 v97, v125, v222
	v_mul_f32_e32 v97, 0x3fb8aa3b, v97
	v_exp_f32_e32 v158, v97
	v_sub_f32_e32 v97, v126, v222
	v_mul_f32_e32 v97, 0x3fb8aa3b, v97
	v_exp_f32_e32 v156, v97
	v_sub_f32_e32 v97, v127, v222
	v_mul_f32_e32 v96, 0x3fb8aa3b, v96
	v_mul_f32_e32 v97, 0x3fb8aa3b, v97
	v_exp_f32_e32 v174, v97
	v_exp_f32_e32 v120, v96
	v_pk_add_f32 v[96:97], v[154:155], v[176:177]
	v_pk_add_f32 v[96:97], v[172:173], v[96:97]
	v_mov_b32_e32 v121, v160
	v_pk_add_f32 v[96:97], v[142:143], v[96:97]
	v_cvt_pk_bf16_f32 v227, v149, v159
	v_pk_add_f32 v[96:97], v[146:147], v[96:97]
	v_pk_mul_f32 v[98:99], v[70:71], v[120:121] op_sel_hi:[1,0]
	v_pk_add_f32 v[96:97], v[144:145], v[96:97]
	v_pk_mul_f32 v[70:71], v[50:51], v[120:121] op_sel_hi:[1,0]
	v_pk_add_f32 v[96:97], v[152:153], v[96:97]
	v_pk_mul_f32 v[50:51], v[74:75], v[120:121] op_sel_hi:[1,0]
	v_pk_add_f32 v[96:97], v[148:149], v[96:97]
	v_pk_add_f32 v[96:97], v[158:159], v[96:97]
	v_pk_add_f32 v[96:97], v[156:157], v[96:97]
	v_pk_mul_f32 v[118:119], v[78:79], v[120:121] op_sel_hi:[1,0]
	v_pk_add_f32 v[96:97], v[174:175], v[96:97]
	v_pk_mul_f32 v[116:117], v[76:77], v[120:121] op_sel_hi:[1,0]
	v_pk_fma_f32 v[132:133], v[132:133], v[120:121], v[96:97]
	v_pk_mul_f32 v[96:97], v[68:69], v[120:121] op_sel_hi:[1,0]
	v_pk_mul_f32 v[78:79], v[54:55], v[120:121] op_sel_hi:[1,0]
	v_pk_mul_f32 v[76:77], v[52:53], v[120:121] op_sel_hi:[1,0]
	v_pk_mul_f32 v[68:69], v[48:49], v[120:121] op_sel_hi:[1,0]
	v_pk_mul_f32 v[48:49], v[72:73], v[120:121] op_sel_hi:[1,0]
	v_pk_mul_f32 v[54:55], v[66:67], v[120:121] op_sel_hi:[1,0]
	v_pk_mul_f32 v[52:53], v[64:65], v[120:121] op_sel_hi:[1,0]
	v_cvt_pk_bf16_f32 v145, v154, v172
	v_cvt_pk_bf16_f32 v153, v128, v129
	v_cvt_pk_bf16_f32 v154, v130, v131
	v_cvt_pk_bf16_f32 v157, v239, v240
	v_cvt_pk_bf16_f32 v240, v142, v146
	v_cvt_pk_bf16_f32 v241, v144, v152
	v_add_u32_e32 v128, 0x1200, v220
	v_add_u32_e32 v129, 32, v220
	v_add_u32_e32 v130, 0x1220, v220
	v_add_u32_e32 v131, 64, v220
	v_add_u32_e32 v142, 0x1240, v220
	v_add_u32_e32 v144, 0x60, v220
	v_pk_mul_f32 v[90:91], v[90:91], v[160:161] op_sel_hi:[1,0]
	v_pk_mul_f32 v[88:89], v[88:89], v[160:161] op_sel_hi:[1,0]
	v_pk_mul_f32 v[86:87], v[86:87], v[160:161] op_sel_hi:[1,0]
	v_pk_mul_f32 v[84:85], v[84:85], v[160:161] op_sel_hi:[1,0]
	v_pk_mul_f32 v[82:83], v[82:83], v[160:161] op_sel_hi:[1,0]
	v_pk_mul_f32 v[80:81], v[80:81], v[160:161] op_sel_hi:[1,0]
	v_pk_mul_f32 v[62:63], v[62:63], v[120:121] op_sel_hi:[1,0]
	v_pk_mul_f32 v[60:61], v[60:61], v[120:121] op_sel_hi:[1,0]
	v_pk_mul_f32 v[58:59], v[58:59], v[120:121] op_sel_hi:[1,0]
	v_pk_mul_f32 v[56:57], v[56:57], v[120:121] op_sel_hi:[1,0]
	v_cvt_pk_bf16_f32 v242, v148, v158
	v_cvt_pk_bf16_f32 v243, v156, v174
	v_add_u32_e32 v146, 0x1260, v220
	ds_read_b64_tr_b16 v[124:125], v220
	ds_read_b64_tr_b16 v[126:127], v128
	ds_read_b64_tr_b16 v[120:121], v129
	ds_read_b64_tr_b16 v[122:123], v130
	ds_read_b64_tr_b16 v[72:73], v131
	ds_read_b64_tr_b16 v[74:75], v142
	ds_read_b64_tr_b16 v[64:65], v144
	ds_read_b64_tr_b16 v[66:67], v146
	s_waitcnt lgkmcnt(0)
	v_mov_b32_e32 v131, v237
	v_mov_b32_e32 v130, v235
	v_perm_b32 v129, v234, v233, s95
	v_perm_b32 v128, v232, v231, s95
	v_mov_b32_e32 v144, v157
	v_mov_b32_e32 v143, v154
	v_mov_b32_e32 v142, v153
	v_mfma_f32_16x16x32_bf16 v[112:115], v[124:127], v[128:131], v[112:115]
	s_nop 0
	v_mfma_f32_16x16x32_bf16 v[116:119], v[124:127], v[142:145], v[116:119]
	v_mfma_f32_16x16x32_bf16 v[124:127], v[120:123], v[128:131], v[108:111]
	v_mfma_f32_16x16x32_bf16 v[96:99], v[120:123], v[142:145], v[96:99]
	v_mfma_f32_16x16x32_bf16 v[120:123], v[72:75], v[128:131], v[104:107]
	v_mfma_f32_16x16x32_bf16 v[72:75], v[72:75], v[142:145], v[76:79]
	v_mfma_f32_16x16x32_bf16 v[146:149], v[64:67], v[128:131], v[100:103]
	v_mfma_f32_16x16x32_bf16 v[64:67], v[64:67], v[142:145], v[68:71]
	v_add_u32_e32 v108, 0x80, v220
	v_add_u32_e32 v109, 0x1280, v220
	v_add_u32_e32 v110, 0xa0, v220
	v_add_u32_e32 v111, 0x12a0, v220
	v_add_u32_e32 v152, 0xc0, v220
	v_add_u32_e32 v153, 0x12c0, v220
	v_add_u32_e32 v154, 0xe0, v220
	v_add_u32_e32 v155, 0x12e0, v220
	ds_read_b64_tr_b16 v[104:105], v108
	ds_read_b64_tr_b16 v[106:107], v109
	ds_read_b64_tr_b16 v[100:101], v110
	ds_read_b64_tr_b16 v[102:103], v111
	ds_read_b64_tr_b16 v[76:77], v152
	ds_read_b64_tr_b16 v[78:79], v153
	ds_read_b64_tr_b16 v[68:69], v154
	ds_read_b64_tr_b16 v[70:71], v155
	s_waitcnt lgkmcnt(0)
	s_nop 0
	v_mfma_f32_16x16x32_bf16 v[88:91], v[100:103], v[128:131], v[88:91]
	v_mfma_f32_16x16x32_bf16 v[84:87], v[76:79], v[128:131], v[84:87]
	v_mfma_f32_16x16x32_bf16 v[60:63], v[76:79], v[142:145], v[60:63]
	v_mfma_f32_16x16x32_bf16 v[80:83], v[68:71], v[128:131], v[80:83]
	v_mfma_f32_16x16x32_bf16 v[56:59], v[68:71], v[142:145], v[56:59]
	v_mfma_f32_16x16x32_bf16 v[152:155], v[104:107], v[128:131], v[92:95]
	v_mfma_f32_16x16x32_bf16 v[156:159], v[104:107], v[142:145], v[48:51]
	v_mfma_f32_16x16x32_bf16 v[172:175], v[100:103], v[142:145], v[52:55]
	s_nop 0
	v_add_u32_e32 v92, 0x2400, v220
	v_add_u32_e32 v93, 0x3600, v220
	v_add_u32_e32 v94, 0x2420, v220
	v_add_u32_e32 v95, 0x3620, v220
	v_add_u32_e32 v100, 0x2440, v220
	v_add_u32_e32 v101, 0x3640, v220
	v_add_u32_e32 v102, 0x2460, v220
	v_add_u32_e32 v103, 0x3660, v220
	ds_read_b64_tr_b16 v[76:77], v92
	ds_read_b64_tr_b16 v[78:79], v93
	ds_read_b64_tr_b16 v[68:69], v94
	ds_read_b64_tr_b16 v[70:71], v95
	ds_read_b64_tr_b16 v[52:53], v100
	ds_read_b64_tr_b16 v[54:55], v101
	ds_read_b64_tr_b16 v[48:49], v102
	ds_read_b64_tr_b16 v[50:51], v103
	s_waitcnt lgkmcnt(0)
	v_mov_b32_e32 v131, v229
	v_mov_b32_e32 v130, v227
	v_mov_b32_e32 v129, v226
	v_mov_b32_e32 v128, v224
	v_mov_b32_e32 v145, v243
	v_mov_b32_e32 v144, v242
	v_mov_b32_e32 v143, v241
	v_mov_b32_e32 v142, v240
	v_mfma_f32_16x16x32_bf16 v[108:111], v[76:79], v[128:131], v[112:115]
	s_nop 0
	v_mfma_f32_16x16x32_bf16 v[76:79], v[76:79], v[142:145], v[116:119]
	v_mfma_f32_16x16x32_bf16 v[104:107], v[68:71], v[128:131], v[124:127]
	v_mfma_f32_16x16x32_bf16 v[68:71], v[68:71], v[142:145], v[96:99]
	v_mfma_f32_16x16x32_bf16 v[100:103], v[52:55], v[128:131], v[120:123]
	v_mfma_f32_16x16x32_bf16 v[52:55], v[52:55], v[142:145], v[72:75]
	v_mfma_f32_16x16x32_bf16 v[92:95], v[48:51], v[128:131], v[146:149]
	v_mfma_f32_16x16x32_bf16 v[48:51], v[48:51], v[142:145], v[64:67]
	v_add_u32_e32 v96, 0x2480, v220
	v_add_u32_e32 v97, 0x3680, v220
	v_add_u32_e32 v98, 0x24a0, v220
	v_add_u32_e32 v99, 0x36a0, v220
	v_add_u32_e32 v120, 0x24c0, v220
	v_add_u32_e32 v121, 0x36c0, v220
	v_add_u32_e32 v122, 0x24e0, v220
	v_add_u32_e32 v123, 0x36e0, v220
	ds_read_b64_tr_b16 v[72:73], v96
	ds_read_b64_tr_b16 v[74:75], v97
	ds_read_b64_tr_b16 v[64:65], v98
	ds_read_b64_tr_b16 v[66:67], v99
	ds_read_b64_tr_b16 v[116:117], v120
	ds_read_b64_tr_b16 v[118:119], v121
	ds_read_b64_tr_b16 v[112:113], v122
	ds_read_b64_tr_b16 v[114:115], v123
	s_waitcnt lgkmcnt(0)
	s_nop 0
	v_mfma_f32_16x16x32_bf16 v[96:99], v[72:75], v[128:131], v[152:155]
	v_mfma_f32_16x16x32_bf16 v[72:75], v[72:75], v[142:145], v[156:159]
	v_mfma_f32_16x16x32_bf16 v[88:91], v[64:67], v[128:131], v[88:91]
	v_mfma_f32_16x16x32_bf16 v[64:67], v[64:67], v[142:145], v[172:175]
	v_mfma_f32_16x16x32_bf16 v[84:87], v[116:119], v[128:131], v[84:87]
	v_mfma_f32_16x16x32_bf16 v[60:63], v[116:119], v[142:145], v[60:63]
	v_mfma_f32_16x16x32_bf16 v[80:83], v[112:115], v[128:131], v[80:83]
	v_mfma_f32_16x16x32_bf16 v[56:59], v[112:115], v[142:145], v[56:59]
	s_add_u32 s36, s36, 0xd0000
	s_addc_u32 s37, s37, 0
	s_add_i32 s22, s22, 1
	s_cmp_lg_u32 s36, 0x340000
	v_mov_b32_e32 v142, v222
	v_mov_b32_e32 v112, v221
	s_barrier
	s_cbranch_scc0 .LBB0_702

.LBB0_754:
	s_mul_i32 s23, s23, 0x8c00
	v_add_u32_e32 v225, s23, v223
	v_add_u32_e32 v113, s23, v224
	ds_read_b128 v[114:117], v113
	ds_read_b128 v[118:121], v113 offset:64
	s_waitcnt lgkmcnt(1)
	v_mfma_f32_16x16x32_bf16 v[156:159], v[114:117], v[0:3], 0
	s_waitcnt lgkmcnt(0)
	v_mfma_f32_16x16x32_bf16 v[156:159], v[118:121], v[4:7], v[156:159]
	ds_read_b128 v[118:121], v113 offset:4416
	s_nop 4
	ds_read_b128 v[114:117], v113 offset:4352
	s_waitcnt lgkmcnt(0)
	v_mfma_f32_16x16x32_bf16 v[172:175], v[114:117], v[0:3], 0
	v_mfma_f32_16x16x32_bf16 v[172:175], v[118:121], v[4:7], v[172:175]
	s_nop 6
	ds_read_b128 v[114:117], v113 offset:8704
	ds_read_b128 v[118:121], v113 offset:8768
	s_waitcnt lgkmcnt(1)
	v_mfma_f32_16x16x32_bf16 v[178:181], v[114:117], v[0:3], 0
	s_waitcnt lgkmcnt(0)
	v_mfma_f32_16x16x32_bf16 v[178:181], v[118:121], v[4:7], v[178:181]
	ds_read_b128 v[118:121], v113 offset:13120
	s_nop 4
	ds_read_b128 v[114:117], v113 offset:13056
	s_waitcnt lgkmcnt(0)
	v_mfma_f32_16x16x32_bf16 v[228:231], v[114:117], v[0:3], 0
	v_mfma_f32_16x16x32_bf16 v[228:231], v[118:121], v[4:7], v[228:231]
	s_nop 6
	ds_read_b128 v[114:117], v113 offset:128
	ds_read_b128 v[118:121], v113 offset:192
	ds_read_b128 v[122:125], v113 offset:4480
	s_waitcnt lgkmcnt(2)
	v_mfma_f32_16x16x32_bf16 v[128:131], v[114:117], v[8:11], 0
	s_waitcnt lgkmcnt(1)
	v_mfma_f32_16x16x32_bf16 v[128:131], v[118:121], v[12:15], v[128:131]
	s_nop 5
	ds_read_b128 v[114:117], v113 offset:4544
	s_waitcnt lgkmcnt(1)
	v_mfma_f32_16x16x32_bf16 v[122:125], v[122:125], v[8:11], 0
	s_waitcnt lgkmcnt(0)
	v_mfma_f32_16x16x32_bf16 v[120:123], v[114:117], v[12:15], v[122:125]
	ds_read_b128 v[114:117], v113 offset:8832
	s_nop 4
	ds_read_b128 v[124:127], v113 offset:8896
	s_waitcnt lgkmcnt(1)
	v_mfma_f32_16x16x32_bf16 v[114:117], v[114:117], v[8:11], 0
	s_waitcnt lgkmcnt(0)
	v_mfma_f32_16x16x32_bf16 v[116:119], v[124:127], v[12:15], v[114:117]
	ds_read_b128 v[124:127], v113 offset:13248
	ds_read_b128 v[182:185], v113 offset:13184
	s_waitcnt lgkmcnt(0)
	v_mfma_f32_16x16x32_bf16 v[182:185], v[182:185], v[8:11], 0
	v_mfma_f32_16x16x32_bf16 v[124:127], v[124:127], v[12:15], v[182:185]
	v_max3_f32 v113, v156, s8, v157
	v_max3_f32 v113, v113, v158, v159
	v_max3_f32 v113, v113, v172, v173
	v_max3_f32 v113, v113, v174, v175
	v_max3_f32 v113, v113, v178, v179
	v_max3_f32 v113, v113, v180, v181
	v_max3_f32 v113, v113, v228, v229
	v_max3_f32 v113, v113, v230, v231
	v_mov_b32_e32 v114, v113
	s_nop 1
	v_permlane32_swap_b32_e32 v114, v113
	s_waitcnt lgkmcnt(0)
	v_max_f32_e32 v114, v114, v114
	v_max_f32_e32 v113, v113, v114
	v_mov_b32_e32 v114, v113
	s_nop 1
	v_permlane16_swap_b32_e32 v114, v113
	s_waitcnt lgkmcnt(0)
	v_max3_f32 v226, v112, v113, v114
	v_sub_f32_e32 v114, v157, v226
	v_mul_f32_e32 v114, 0x3fb8aa3b, v114
	v_exp_f32_e32 v176, v114
	v_sub_f32_e32 v114, v158, v226
	v_sub_f32_e32 v113, v156, v226
	v_mul_f32_e32 v114, 0x3fb8aa3b, v114
	v_mul_f32_e32 v113, 0x3fb8aa3b, v113
	v_exp_f32_e32 v158, v114
	v_sub_f32_e32 v114, v159, v226
	v_exp_f32_e32 v156, v113
	v_mul_f32_e32 v114, 0x3fb8aa3b, v114
	v_exp_f32_e32 v182, v114
	v_sub_f32_e32 v114, v172, v226
	v_mul_f32_e32 v114, 0x3fb8aa3b, v114
	v_exp_f32_e32 v172, v114
	v_sub_f32_e32 v114, v173, v226
	v_add_f32_e32 v113, 0, v156
	v_mul_f32_e32 v114, 0x3fb8aa3b, v114
	v_add_f32_e32 v113, v176, v113
	v_exp_f32_e32 v184, v114
	v_add_f32_e32 v113, v158, v113
	v_add_f32_e32 v113, v182, v113
	v_add_f32_e32 v113, v172, v113
	v_add_f32_e32 v187, v184, v113
	v_sub_f32_e32 v113, v174, v226
	v_mul_f32_e32 v113, 0x3fb8aa3b, v113
	v_exp_f32_e32 v177, v113
	v_sub_f32_e32 v113, v175, v226
	v_mul_f32_e32 v113, 0x3fb8aa3b, v113
	v_exp_f32_e32 v183, v113
	v_sub_f32_e32 v113, v178, v226
	v_mul_f32_e32 v113, 0x3fb8aa3b, v113
	v_exp_f32_e32 v155, v113
	v_sub_f32_e32 v113, v179, v226
	v_mul_f32_e32 v113, 0x3fb8aa3b, v113
	v_exp_f32_e32 v159, v113
	v_sub_f32_e32 v113, v180, v226
	v_mul_f32_e32 v113, 0x3fb8aa3b, v113
	v_exp_f32_e32 v157, v113
	v_sub_f32_e32 v113, v181, v226
	v_mul_f32_e32 v113, 0x3fb8aa3b, v113
	v_exp_f32_e32 v175, v113
	v_sub_f32_e32 v113, v228, v226
	v_mul_f32_e32 v113, 0x3fb8aa3b, v113
	v_exp_f32_e32 v173, v113
	v_sub_f32_e32 v113, v229, v226
	v_mul_f32_e32 v113, 0x3fb8aa3b, v113
	v_exp_f32_e32 v181, v113
	v_sub_f32_e32 v113, v230, v226
	v_sub_f32_e32 v112, v112, v226
	v_mul_f32_e32 v113, 0x3fb8aa3b, v113
	v_mul_f32_e32 v112, 0x3fb8aa3b, v112
	v_exp_f32_e32 v179, v113
	v_sub_f32_e32 v113, v231, v226
	v_mul_f32_e32 v113, 0x3fb8aa3b, v113
	v_exp_f32_e32 v160, v112
	v_exp_f32_e32 v185, v113
	v_pk_mul_f32 v[112:113], v[108:109], v[160:161] op_sel_hi:[1,0]
	v_pk_mul_f32 v[108:109], v[104:105], v[160:161] op_sel_hi:[1,0]
	v_pk_mul_f32 v[104:105], v[100:101], v[160:161] op_sel_hi:[1,0]
	v_pk_mul_f32 v[100:101], v[92:93], v[160:161] op_sel_hi:[1,0]
	v_pk_mul_f32 v[92:93], v[96:97], v[160:161] op_sel_hi:[1,0]
	v_max3_f32 v96, v128, s8, v129
	v_max3_f32 v96, v96, v130, v131
	v_max3_f32 v96, v96, v120, v121
	v_max3_f32 v96, v96, v122, v123
	v_max3_f32 v96, v96, v116, v117
	v_max3_f32 v96, v96, v118, v119
	v_max3_f32 v96, v96, v124, v125
	v_cvt_pk_bf16_f32 v242, v177, v183
	v_max3_f32 v96, v96, v126, v127
	v_cvt_pk_bf16_f32 v234, v179, v185
	v_mov_b32_e32 v97, v96
	s_nop 1
	v_permlane32_swap_b32_e32 v97, v96
	v_pk_mul_f32 v[114:115], v[110:111], v[160:161] op_sel_hi:[1,0]
	v_pk_mul_f32 v[110:111], v[106:107], v[160:161] op_sel_hi:[1,0]
	v_pk_mul_f32 v[106:107], v[102:103], v[160:161] op_sel_hi:[1,0]
	v_pk_mul_f32 v[102:103], v[94:95], v[160:161] op_sel_hi:[1,0]
	s_waitcnt lgkmcnt(0)
	v_max_f32_e32 v97, v97, v97
	v_max_f32_e32 v96, v96, v97
	v_mov_b32_e32 v97, v96
	s_nop 1
	v_permlane16_swap_b32_e32 v97, v96
	v_pk_mul_f32 v[94:95], v[98:99], v[160:161] op_sel_hi:[1,0]
	s_waitcnt lgkmcnt(0)
	v_max3_f32 v227, v154, v96, v97
	v_sub_f32_e32 v98, v129, v227
	v_mul_f32_e32 v98, 0x3fb8aa3b, v98
	v_exp_f32_e32 v129, v98
	v_sub_f32_e32 v98, v130, v227
	v_sub_f32_e32 v97, v128, v227
	v_mul_f32_e32 v98, 0x3fb8aa3b, v98
	v_mul_f32_e32 v97, 0x3fb8aa3b, v97
	v_exp_f32_e32 v130, v98
	v_sub_f32_e32 v98, v131, v227
	v_exp_f32_e32 v128, v97
	v_mul_f32_e32 v98, 0x3fb8aa3b, v98
	v_exp_f32_e32 v131, v98
	v_sub_f32_e32 v98, v120, v227
	v_mul_f32_e32 v98, 0x3fb8aa3b, v98
	v_exp_f32_e32 v244, v98
	v_sub_f32_e32 v98, v121, v227
	v_add_f32_e32 v97, 0, v128
	v_mul_f32_e32 v98, 0x3fb8aa3b, v98
	v_add_f32_e32 v97, v129, v97
	v_exp_f32_e32 v245, v98
	v_add_f32_e32 v97, v130, v97
	v_add_f32_e32 v97, v131, v97
	v_add_f32_e32 v97, v244, v97
	v_add_f32_e32 v186, v245, v97
	v_sub_f32_e32 v97, v122, v227
	v_mul_f32_e32 v97, 0x3fb8aa3b, v97
	v_cvt_pk_bf16_f32 v237, v156, v176
	v_exp_f32_e32 v176, v97
	v_sub_f32_e32 v97, v123, v227
	v_bfe_u32 v174, v182, 16, 1
	v_mul_f32_e32 v97, 0x3fb8aa3b, v97
	v_add3_u32 v239, v182, v174, s94
	v_exp_f32_e32 v182, v97
	v_sub_f32_e32 v97, v116, v227
	v_mul_f32_e32 v97, 0x3fb8aa3b, v97
	v_bfe_u32 v178, v158, 16, 1
	v_sub_f32_e32 v96, v154, v227
	v_exp_f32_e32 v154, v97
	v_sub_f32_e32 v97, v117, v227
	v_add3_u32 v238, v158, v178, s94
	v_mul_f32_e32 v97, 0x3fb8aa3b, v97
	v_exp_f32_e32 v158, v97
	v_sub_f32_e32 v97, v118, v227
	v_mul_f32_e32 v97, 0x3fb8aa3b, v97
	v_cvt_pk_bf16_f32 v231, v157, v175
	v_exp_f32_e32 v156, v97
	v_sub_f32_e32 v97, v119, v227
	v_mul_f32_e32 v97, 0x3fb8aa3b, v97
	v_exp_f32_e32 v174, v97
	v_sub_f32_e32 v97, v124, v227
	v_cvt_pk_bf16_f32 v240, v172, v184
	v_mul_f32_e32 v97, 0x3fb8aa3b, v97
	v_cvt_pk_bf16_f32 v229, v155, v159
	v_exp_f32_e32 v172, v97
	v_sub_f32_e32 v97, v125, v227
	v_mul_f32_e32 v97, 0x3fb8aa3b, v97
	v_exp_f32_e32 v180, v97
	v_sub_f32_e32 v97, v126, v227
	v_mul_f32_e32 v97, 0x3fb8aa3b, v97
	v_exp_f32_e32 v178, v97
	v_sub_f32_e32 v97, v127, v227
	v_mul_f32_e32 v96, 0x3fb8aa3b, v96
	v_mul_f32_e32 v97, 0x3fb8aa3b, v97
	v_exp_f32_e32 v184, v97
	v_exp_f32_e32 v120, v96
	v_pk_add_f32 v[96:97], v[176:177], v[186:187]
	v_pk_add_f32 v[96:97], v[182:183], v[96:97]
	v_mov_b32_e32 v121, v160
	v_pk_add_f32 v[96:97], v[154:155], v[96:97]
	v_cvt_pk_bf16_f32 v232, v173, v181
	v_pk_add_f32 v[96:97], v[158:159], v[96:97]
	v_pk_mul_f32 v[98:99], v[62:63], v[120:121] op_sel_hi:[1,0]
	v_pk_add_f32 v[96:97], v[156:157], v[96:97]
	v_pk_mul_f32 v[62:63], v[34:35], v[120:121] op_sel_hi:[1,0]
	v_pk_add_f32 v[96:97], v[174:175], v[96:97]
	v_pk_mul_f32 v[34:35], v[74:75], v[120:121] op_sel_hi:[1,0]
	v_pk_add_f32 v[96:97], v[172:173], v[96:97]
	v_pk_add_f32 v[96:97], v[180:181], v[96:97]
	v_pk_add_f32 v[96:97], v[178:179], v[96:97]
	v_pk_mul_f32 v[90:91], v[90:91], v[160:161] op_sel_hi:[1,0]
	v_pk_add_f32 v[96:97], v[184:185], v[96:97]
	v_pk_mul_f32 v[88:89], v[88:89], v[160:161] op_sel_hi:[1,0]
	v_pk_mul_f32 v[86:87], v[86:87], v[160:161] op_sel_hi:[1,0]
	v_pk_mul_f32 v[84:85], v[84:85], v[160:161] op_sel_hi:[1,0]
	v_pk_mul_f32 v[82:83], v[82:83], v[160:161] op_sel_hi:[1,0]
	v_pk_mul_f32 v[80:81], v[80:81], v[160:161] op_sel_hi:[1,0]
	v_pk_fma_f32 v[142:143], v[142:143], v[120:121], v[96:97]
	v_pk_mul_f32 v[118:119], v[78:79], v[120:121] op_sel_hi:[1,0]
	v_pk_mul_f32 v[116:117], v[76:77], v[120:121] op_sel_hi:[1,0]
	v_pk_mul_f32 v[96:97], v[60:61], v[120:121] op_sel_hi:[1,0]
	v_pk_mul_f32 v[78:79], v[46:47], v[120:121] op_sel_hi:[1,0]
	v_pk_mul_f32 v[76:77], v[44:45], v[120:121] op_sel_hi:[1,0]
	v_pk_mul_f32 v[60:61], v[32:33], v[120:121] op_sel_hi:[1,0]
	v_pk_mul_f32 v[32:33], v[72:73], v[120:121] op_sel_hi:[1,0]
	v_pk_mul_f32 v[46:47], v[58:59], v[120:121] op_sel_hi:[1,0]
	v_pk_mul_f32 v[44:45], v[56:57], v[120:121] op_sel_hi:[1,0]
	v_cvt_pk_bf16_f32 v173, v128, v129
	v_cvt_pk_bf16_f32 v175, v130, v131
	v_cvt_pk_bf16_f32 v177, v244, v245
	v_cvt_pk_bf16_f32 v247, v154, v158
	v_cvt_pk_bf16_f32 v248, v156, v174
	v_add_u32_e32 v128, 0x1200, v225
	v_add_u32_e32 v129, 32, v225
	v_add_u32_e32 v130, 0x1220, v225
	v_add_u32_e32 v131, 64, v225
	v_add_u32_e32 v154, 0x1240, v225
	v_add_u32_e32 v156, 0x60, v225
	v_pk_mul_f32 v[54:55], v[54:55], v[120:121] op_sel_hi:[1,0]
	v_pk_mul_f32 v[52:53], v[52:53], v[120:121] op_sel_hi:[1,0]
	v_pk_mul_f32 v[50:51], v[50:51], v[120:121] op_sel_hi:[1,0]
	v_pk_mul_f32 v[48:49], v[48:49], v[120:121] op_sel_hi:[1,0]
	v_cvt_pk_bf16_f32 v249, v172, v180
	v_cvt_pk_bf16_f32 v250, v178, v184
	v_add_u32_e32 v172, 0x1260, v225
	ds_read_b64_tr_b16 v[124:125], v225
	ds_read_b64_tr_b16 v[126:127], v128
	ds_read_b64_tr_b16 v[120:121], v129
	ds_read_b64_tr_b16 v[122:123], v130
	ds_read_b64_tr_b16 v[72:73], v131
	ds_read_b64_tr_b16 v[74:75], v154
	ds_read_b64_tr_b16 v[56:57], v156
	ds_read_b64_tr_b16 v[58:59], v172
	s_waitcnt lgkmcnt(0)
	v_mov_b32_e32 v131, v242
	v_mov_b32_e32 v130, v240
	v_perm_b32 v129, v239, v238, s95
	v_mov_b32_e32 v128, v237
	v_mov_b32_e32 v156, v177
	v_mov_b32_e32 v155, v175
	v_mov_b32_e32 v154, v173
	v_cvt_pk_bf16_f32 v157, v176, v182
	v_mfma_f32_16x16x32_bf16 v[112:115], v[124:127], v[128:131], v[112:115]
	s_nop 0
	v_mfma_f32_16x16x32_bf16 v[116:119], v[124:127], v[154:157], v[116:119]
	v_mfma_f32_16x16x32_bf16 v[124:127], v[120:123], v[128:131], v[108:111]
	v_mfma_f32_16x16x32_bf16 v[96:99], v[120:123], v[154:157], v[96:99]
	v_mfma_f32_16x16x32_bf16 v[120:123], v[72:75], v[128:131], v[104:107]
	v_mfma_f32_16x16x32_bf16 v[72:75], v[72:75], v[154:157], v[76:79]
	v_mfma_f32_16x16x32_bf16 v[172:175], v[56:59], v[128:131], v[100:103]
	v_mfma_f32_16x16x32_bf16 v[56:59], v[56:59], v[154:157], v[60:63]
	v_add_u32_e32 v108, 0x80, v225
	v_add_u32_e32 v109, 0x1280, v225
	v_add_u32_e32 v110, 0xa0, v225
	v_add_u32_e32 v111, 0x12a0, v225
	v_add_u32_e32 v159, 0xc0, v225
	v_add_u32_e32 v160, 0x12c0, v225
	v_add_u32_e32 v176, 0xe0, v225
	v_add_u32_e32 v177, 0x12e0, v225
	ds_read_b64_tr_b16 v[104:105], v108
	ds_read_b64_tr_b16 v[106:107], v109
	ds_read_b64_tr_b16 v[100:101], v110
	ds_read_b64_tr_b16 v[102:103], v111
	ds_read_b64_tr_b16 v[76:77], v159
	ds_read_b64_tr_b16 v[78:79], v160
	ds_read_b64_tr_b16 v[60:61], v176
	ds_read_b64_tr_b16 v[62:63], v177
	s_waitcnt lgkmcnt(0)
	s_nop 0
	v_mfma_f32_16x16x32_bf16 v[88:91], v[100:103], v[128:131], v[88:91]
	v_mfma_f32_16x16x32_bf16 v[84:87], v[76:79], v[128:131], v[84:87]
	v_mfma_f32_16x16x32_bf16 v[52:55], v[76:79], v[154:157], v[52:55]
	v_mfma_f32_16x16x32_bf16 v[80:83], v[60:63], v[128:131], v[80:83]
	v_mfma_f32_16x16x32_bf16 v[48:51], v[60:63], v[154:157], v[48:51]
	v_mfma_f32_16x16x32_bf16 v[176:179], v[104:107], v[128:131], v[92:95]
	v_mfma_f32_16x16x32_bf16 v[180:183], v[104:107], v[154:157], v[32:35]
	v_mfma_f32_16x16x32_bf16 v[184:187], v[100:103], v[154:157], v[44:47]
	s_nop 0
	v_add_u32_e32 v92, 0x2400, v225
	v_add_u32_e32 v93, 0x3600, v225
	v_add_u32_e32 v94, 0x2420, v225
	v_add_u32_e32 v95, 0x3620, v225
	v_add_u32_e32 v100, 0x2440, v225
	v_add_u32_e32 v101, 0x3640, v225
	v_add_u32_e32 v102, 0x2460, v225
	v_add_u32_e32 v103, 0x3660, v225
	ds_read_b64_tr_b16 v[76:77], v92
	ds_read_b64_tr_b16 v[78:79], v93
	ds_read_b64_tr_b16 v[60:61], v94
	ds_read_b64_tr_b16 v[62:63], v95
	ds_read_b64_tr_b16 v[44:45], v100
	ds_read_b64_tr_b16 v[46:47], v101
	ds_read_b64_tr_b16 v[32:33], v102
	ds_read_b64_tr_b16 v[34:35], v103
	s_waitcnt lgkmcnt(0)
	v_mov_b32_e32 v131, v234
	v_mov_b32_e32 v130, v232
	v_mov_b32_e32 v129, v231
	v_mov_b32_e32 v128, v229
	v_mov_b32_e32 v157, v250
	v_mov_b32_e32 v156, v249
	v_mov_b32_e32 v155, v248
	v_mov_b32_e32 v154, v247
	v_mfma_f32_16x16x32_bf16 v[108:111], v[76:79], v[128:131], v[112:115]
	s_nop 0
	v_mfma_f32_16x16x32_bf16 v[76:79], v[76:79], v[154:157], v[116:119]
	v_mfma_f32_16x16x32_bf16 v[104:107], v[60:63], v[128:131], v[124:127]
	v_mfma_f32_16x16x32_bf16 v[60:63], v[60:63], v[154:157], v[96:99]
	v_mfma_f32_16x16x32_bf16 v[100:103], v[44:47], v[128:131], v[120:123]
	v_mfma_f32_16x16x32_bf16 v[44:47], v[44:47], v[154:157], v[72:75]
	v_mfma_f32_16x16x32_bf16 v[92:95], v[32:35], v[128:131], v[172:175]
	v_mfma_f32_16x16x32_bf16 v[32:35], v[32:35], v[154:157], v[56:59]
	v_add_u32_e32 v96, 0x2480, v225
	v_add_u32_e32 v97, 0x3680, v225
	v_add_u32_e32 v98, 0x24a0, v225
	v_add_u32_e32 v99, 0x36a0, v225
	v_add_u32_e32 v120, 0x24c0, v225
	v_add_u32_e32 v121, 0x36c0, v225
	v_add_u32_e32 v122, 0x24e0, v225
	v_add_u32_e32 v123, 0x36e0, v225
	ds_read_b64_tr_b16 v[72:73], v96
	ds_read_b64_tr_b16 v[74:75], v97
	ds_read_b64_tr_b16 v[56:57], v98
	ds_read_b64_tr_b16 v[58:59], v99
	ds_read_b64_tr_b16 v[116:117], v120
	ds_read_b64_tr_b16 v[118:119], v121
	ds_read_b64_tr_b16 v[112:113], v122
	ds_read_b64_tr_b16 v[114:115], v123
	s_waitcnt lgkmcnt(0)
	s_nop 0
	v_mfma_f32_16x16x32_bf16 v[96:99], v[72:75], v[128:131], v[176:179]
	v_mfma_f32_16x16x32_bf16 v[72:75], v[72:75], v[154:157], v[180:183]
	v_mfma_f32_16x16x32_bf16 v[88:91], v[56:59], v[128:131], v[88:91]
	v_mfma_f32_16x16x32_bf16 v[56:59], v[56:59], v[154:157], v[184:187]
	v_mfma_f32_16x16x32_bf16 v[84:87], v[116:119], v[128:131], v[84:87]
	v_mfma_f32_16x16x32_bf16 v[52:55], v[116:119], v[154:157], v[52:55]
	v_mfma_f32_16x16x32_bf16 v[80:83], v[112:115], v[128:131], v[80:83]
	v_mfma_f32_16x16x32_bf16 v[48:51], v[112:115], v[154:157], v[48:51]
	s_add_u32 s38, s38, 0x10000
	s_addc_u32 s39, s39, 0
	s_add_i32 s22, s22, 1
	v_add_u32_e32 v133, 64, v133
	v_add_u32_e32 v135, 64, v135
	v_add_u32_e32 v137, 64, v137
	v_add_u32_e32 v139, 64, v139
	s_cmp_lg_u32 s38, 0x180000
	v_mov_b32_e32 v154, v227
	v_mov_b32_e32 v112, v226
	s_barrier
	s_cbranch_scc0 .LBB0_773
